# prompt cross-attention tasks moved off the 96 recurrence workgroups (workgroup 96+k takes tasks k and k+160)
# speedup vs baseline: 1.0214x; 1.0011x over previous
; __device__ __forceinline__ void p2_xattn_prompt(const Params& P, unsigned char* lds) {
;     using namespace sba;
;     const int tid = threadIdx.x, lane = tid & 63, r32 = lane & 31, hi = lane >> 5; const int wid = __builtin_amdgcn_readfirstlane(tid >> 6);
;     const bf16_t* xq = (const bf16_t*)(P.ws + WS_XQ); const bf16_t* gate = (const bf16_t*)(P.ws + WS_GATE); bf16_t* O = (bf16_t*)(P.ws + WS_O);
;     const float* MK = P.out + OUT_MK_P; const float* MV = P.out + OUT_MV_P;
;     for (int task = blockIdx.x; task < NB * XH * 16; task += gridDim.x) {
;         const int qblk = task & 15, h = (task >> 4) & 3, b = task >> 6;
;         __syncthreads();
.LBB0_905:
	s_add_u32 s0, s78, 0x7a34000
	s_addc_u32 s1, s79, 0
	s_cmpk_lt_i32 s56, 0x60
	v_readfirstlane_b32 s2, v0
	s_cbranch_scc1 .LBB0_912
	s_add_u32 s14, s76, 0x7185000
	s_addc_u32 s15, s77, 0
	s_lshr_b32 s2, s2, 1
	v_and_b32_e32 v4, 31, v0
	s_and_b32 s2, s2, 0x7fffffe0
	v_or_b32_e32 v1, s2, v4
	v_lshlrev_b32_e32 v7, 4, v4
	v_lshlrev_b32_e32 v4, 1, v0
	v_and_b32_e32 v4, 32, v4
	v_bfe_u32 v3, v0, 5, 1
	v_add_u32_e32 v6, 0, v4
	v_lshlrev_b32_e32 v4, 3, v0
	v_and_b32_e32 v8, 24, v4
	v_lshlrev_b32_e32 v4, 2, v3
	v_lshrrev_b32_e32 v146, 2, v0
	v_lshlrev_b32_e32 v2, 3, v3
	v_lshl_add_u32 v5, v3, 10, 0
	v_and_or_b32 v3, v146, 3, v4
	v_lshlrev_b32_e32 v3, 6, v3
	v_add3_u32 v147, v6, v8, v3
	v_and_b32_e32 v3, 3, v0
	v_lshlrev_b32_e32 v6, 3, v3
	v_lshlrev_b32_e32 v148, 4, v3
	v_lshlrev_b32_e32 v3, 7, v0
	v_lshlrev_b32_e32 v8, 2, v0
	v_and_b32_e32 v9, 63, v0
	s_load_dword s16, s[58:59], 0xf8
	v_and_b32_e32 v3, 0x6000, v3
	v_and_b32_e32 v8, 0x400, v8
	v_lshlrev_b32_e32 v9, 4, v9
	v_or3_b32 v3, v3, v8, v9
	v_add_u32_e32 v150, 0, v3
	v_lshrrev_b32_e32 v3, 3, v0
	v_mov_b32_e32 v135, 0
	v_and_b32_e32 v134, 32, v3
	v_lshl_add_u64 v[8:9], s[76:77], 0, v[134:135]
	s_mov_b64 s[4:5], 0x7085010
	s_mov_b32 s3, 0
	v_or_b32_e32 v149, 0xfffffe00, v0
	v_lshl_add_u64 v[136:137], v[8:9], 0, s[4:5]
	s_lshl_b32 s17, s56, 2
	s_waitcnt lgkmcnt(0)
	s_lshl_b32 s18, s16, 2
	v_lshlrev_b32_e32 v151, 6, v146
	v_lshlrev_b32_e32 v152, 7, v146
	s_movk_i32 s19, 0x5ff
	v_lshlrev_b32_e32 v138, 2, v6
	v_mov_b32_e32 v139, v135
	v_lshlrev_b32_e32 v140, 1, v2
	v_add_u32_e32 v153, v5, v7
	v_lshlrev_b32_e32 v142, 1, v4
	s_mov_b64 s[4:5], 0x8254600
	s_mov_b32 s20, 0x8254000
	s_mov_b64 s[6:7], 0x14ca9200
	s_mov_b32 s21, 0x14ca9000
	s_sub_i32 s22, s56, 0x60
	s_lshl_b32 s17, s22, 2
	s_movk_i32 s16, 0xa0
	s_lshl_b32 s18, s16, 2
